# diff attention epilogue: 16 row-per-lane dwordx2 stores widened to 8 dwordx4 with v_permlane32_swap pairs (same bytes to the same addresses), counted vmcnt waits re-derived
# baseline (speedup 1.0000x reference)
.LBB0_494:
	s_or_b64 exec, exec, s[0:1]
	s_waitcnt lgkmcnt(0)
	s_barrier
	s_and_saveexec_b64 s[40:41], vcc
	s_cbranch_execz .LBB0_460
	ds_read2st64_b32 v[72:73], v70 offset1:1
	v_mov_b32_e32 v74, v50
	v_mov_b32_e32 v75, v66
	s_load_dwordx2 s[0:1], s[66:67], 0x40
	s_waitcnt lgkmcnt(0)
	v_mov_b32_e32 v69, v72
	v_pk_mul_f32 v[74:75], v[74:75], v[68:69]
	v_mov_b32_e32 v69, v73
	v_sub_f32_e32 v50, v74, v75
	v_mov_b32_e32 v74, v51
	v_mov_b32_e32 v75, v66
	v_pk_mul_f32 v[72:73], v[74:75], v[68:69]
	v_mov_b32_e32 v74, v52
	v_sub_f32_e32 v51, v72, v73
	ds_read2st64_b32 v[72:73], v70 offset0:2 offset1:3
	s_add_u32 s0, s0, s56
	s_addc_u32 s1, s1, s57
	s_waitcnt lgkmcnt(0)
	v_mov_b32_e32 v69, v72
	v_pk_mul_f32 v[74:75], v[74:75], v[68:69]
	v_mov_b32_e32 v69, v73
	v_sub_f32_e32 v52, v74, v75
	v_mov_b32_e32 v74, v53
	v_mov_b32_e32 v75, v66
	v_pk_mul_f32 v[72:73], v[74:75], v[68:69]
	v_mov_b32_e32 v74, v54
	v_sub_f32_e32 v53, v72, v73
	ds_read2st64_b32 v[72:73], v70 offset0:4 offset1:5
	s_waitcnt lgkmcnt(0)
	v_mov_b32_e32 v69, v72
	v_pk_mul_f32 v[74:75], v[74:75], v[68:69]
	v_mov_b32_e32 v69, v73
	v_sub_f32_e32 v54, v74, v75
	v_mov_b32_e32 v74, v55
	v_mov_b32_e32 v75, v66
	v_pk_mul_f32 v[72:73], v[74:75], v[68:69]
	v_mov_b32_e32 v74, v56
	v_sub_f32_e32 v55, v72, v73
	ds_read2st64_b32 v[72:73], v70 offset0:6 offset1:7
	s_waitcnt lgkmcnt(0)
	v_mov_b32_e32 v69, v72
	v_pk_mul_f32 v[74:75], v[74:75], v[68:69]
	v_mov_b32_e32 v69, v73
	v_sub_f32_e32 v56, v74, v75
	v_mov_b32_e32 v74, v57
	v_mov_b32_e32 v75, v66
	v_pk_mul_f32 v[72:73], v[74:75], v[68:69]
	v_mov_b32_e32 v74, v58
	v_sub_f32_e32 v57, v72, v73
	ds_read2st64_b32 v[72:73], v70 offset0:8 offset1:9
	s_waitcnt lgkmcnt(0)
	v_mov_b32_e32 v69, v72
	v_pk_mul_f32 v[74:75], v[74:75], v[68:69]
	v_mov_b32_e32 v69, v73
	v_sub_f32_e32 v58, v74, v75
	v_mov_b32_e32 v74, v59
	v_mov_b32_e32 v75, v66
	v_pk_mul_f32 v[72:73], v[74:75], v[68:69]
	v_mov_b32_e32 v74, v60
	v_sub_f32_e32 v59, v72, v73
	ds_read2st64_b32 v[72:73], v70 offset0:10 offset1:11
	s_waitcnt lgkmcnt(0)
	v_mov_b32_e32 v69, v72
	v_pk_mul_f32 v[74:75], v[74:75], v[68:69]
	v_mov_b32_e32 v69, v73
	v_sub_f32_e32 v60, v74, v75
	v_mov_b32_e32 v74, v61
	v_mov_b32_e32 v75, v66
	v_pk_mul_f32 v[72:73], v[74:75], v[68:69]
	v_mov_b32_e32 v74, v62
	v_sub_f32_e32 v61, v72, v73
	ds_read2st64_b32 v[72:73], v70 offset0:12 offset1:13
	s_waitcnt lgkmcnt(0)
	v_mov_b32_e32 v69, v72
	v_pk_mul_f32 v[74:75], v[74:75], v[68:69]
	v_mov_b32_e32 v69, v73
	v_sub_f32_e32 v62, v74, v75
	v_mov_b32_e32 v74, v63
	v_mov_b32_e32 v75, v66
	v_pk_mul_f32 v[72:73], v[74:75], v[68:69]
	v_mov_b32_e32 v74, v64
	v_sub_f32_e32 v63, v72, v73
	ds_read2st64_b32 v[72:73], v70 offset0:14 offset1:15
	s_waitcnt lgkmcnt(0)
	v_mov_b32_e32 v69, v72
	v_pk_mul_f32 v[74:75], v[74:75], v[68:69]
	v_mov_b32_e32 v69, v73
	v_sub_f32_e32 v64, v74, v75
	v_mov_b32_e32 v74, v65
	v_mov_b32_e32 v75, v66
	v_pk_mul_f32 v[72:73], v[74:75], v[68:69]
	v_mov_b32_e32 v74, v34
	v_sub_f32_e32 v65, v72, v73
	ds_read2st64_b32 v[72:73], v70 offset0:16 offset1:17
	s_waitcnt lgkmcnt(0)
	v_mov_b32_e32 v69, v72
	v_pk_mul_f32 v[74:75], v[74:75], v[68:69]
	v_mov_b32_e32 v69, v73
	v_sub_f32_e32 v34, v74, v75
	v_mov_b32_e32 v74, v35
	v_mov_b32_e32 v75, v66
	v_pk_mul_f32 v[72:73], v[74:75], v[68:69]
	v_mov_b32_e32 v74, v36
	v_sub_f32_e32 v35, v72, v73
	ds_read2st64_b32 v[72:73], v70 offset0:18 offset1:19
	s_waitcnt lgkmcnt(0)
	v_mov_b32_e32 v69, v72
	v_pk_mul_f32 v[74:75], v[74:75], v[68:69]
	v_mov_b32_e32 v69, v73
	v_sub_f32_e32 v36, v74, v75
	v_mov_b32_e32 v74, v37
	v_mov_b32_e32 v75, v66
	v_pk_mul_f32 v[72:73], v[74:75], v[68:69]
	v_mov_b32_e32 v74, v38
	v_sub_f32_e32 v37, v72, v73
	ds_read2st64_b32 v[72:73], v70 offset0:20 offset1:21
	s_waitcnt lgkmcnt(0)
	v_mov_b32_e32 v69, v72
	v_pk_mul_f32 v[74:75], v[74:75], v[68:69]
	v_mov_b32_e32 v69, v73
	v_sub_f32_e32 v38, v74, v75
	v_mov_b32_e32 v74, v39
	v_mov_b32_e32 v75, v66
	v_pk_mul_f32 v[72:73], v[74:75], v[68:69]
	v_mov_b32_e32 v74, v40
	v_sub_f32_e32 v39, v72, v73
	ds_read2st64_b32 v[72:73], v70 offset0:22 offset1:23
	s_waitcnt lgkmcnt(0)
	v_mov_b32_e32 v69, v72
	v_pk_mul_f32 v[74:75], v[74:75], v[68:69]
	v_mov_b32_e32 v69, v73
	v_sub_f32_e32 v40, v74, v75
	v_mov_b32_e32 v74, v41
	v_mov_b32_e32 v75, v66
	v_pk_mul_f32 v[72:73], v[74:75], v[68:69]
	v_mov_b32_e32 v74, v42
	v_sub_f32_e32 v41, v72, v73
	ds_read2st64_b32 v[72:73], v70 offset0:24 offset1:25
	s_waitcnt lgkmcnt(0)
	v_mov_b32_e32 v69, v72
	v_pk_mul_f32 v[74:75], v[74:75], v[68:69]
	v_mov_b32_e32 v69, v73
	v_sub_f32_e32 v42, v74, v75
	v_mov_b32_e32 v74, v43
	v_mov_b32_e32 v75, v66
	v_pk_mul_f32 v[72:73], v[74:75], v[68:69]
	v_mov_b32_e32 v74, v44
	v_sub_f32_e32 v43, v72, v73
	ds_read2st64_b32 v[72:73], v70 offset0:26 offset1:27
	s_waitcnt lgkmcnt(0)
	v_mov_b32_e32 v69, v72
	v_pk_mul_f32 v[74:75], v[74:75], v[68:69]
	v_mov_b32_e32 v69, v73
	v_sub_f32_e32 v44, v74, v75
	v_mov_b32_e32 v74, v45
	v_mov_b32_e32 v75, v66
	v_pk_mul_f32 v[72:73], v[74:75], v[68:69]
	v_mov_b32_e32 v74, v46
	v_sub_f32_e32 v45, v72, v73
	ds_read2st64_b32 v[72:73], v70 offset0:28 offset1:29
	s_waitcnt lgkmcnt(0)
	v_mov_b32_e32 v69, v72
	v_pk_mul_f32 v[74:75], v[74:75], v[68:69]
	v_mov_b32_e32 v69, v73
	v_sub_f32_e32 v46, v74, v75
	v_mov_b32_e32 v74, v47
	v_mov_b32_e32 v75, v66
	v_pk_mul_f32 v[72:73], v[74:75], v[68:69]
	v_mov_b32_e32 v74, v48
	v_sub_f32_e32 v47, v72, v73
	ds_read2st64_b32 v[72:73], v70 offset0:30 offset1:31
	s_waitcnt lgkmcnt(0)
	v_mov_b32_e32 v69, v72
	v_pk_mul_f32 v[74:75], v[74:75], v[68:69]
	v_mov_b32_e32 v69, v73
	v_sub_f32_e32 v48, v74, v75
	v_mov_b32_e32 v74, v49
	v_mov_b32_e32 v75, v66
	v_pk_mul_f32 v[72:73], v[74:75], v[68:69]
	v_mov_b32_e32 v74, v18
	v_sub_f32_e32 v49, v72, v73
	ds_read2st64_b32 v[72:73], v70 offset0:32 offset1:33
	v_mov_b32_e32 v18, v19
	v_mov_b32_e32 v19, v66
	s_waitcnt lgkmcnt(0)
	v_mov_b32_e32 v69, v72
	v_pk_mul_f32 v[74:75], v[74:75], v[68:69]
	v_mov_b32_e32 v69, v73
	v_pk_mul_f32 v[18:19], v[18:19], v[68:69]
	v_sub_f32_e32 v71, v74, v75
	v_sub_f32_e32 v72, v18, v19
	ds_read2st64_b32 v[18:19], v70 offset0:34 offset1:35
	v_mov_b32_e32 v74, v20
	v_mov_b32_e32 v75, v66
	v_mov_b32_e32 v20, v21
	v_mov_b32_e32 v21, v66
	s_waitcnt lgkmcnt(0)
	v_mov_b32_e32 v69, v18
	v_pk_mul_f32 v[74:75], v[74:75], v[68:69]
	v_mov_b32_e32 v69, v19
	v_pk_mul_f32 v[18:19], v[20:21], v[68:69]
	v_sub_f32_e32 v73, v74, v75
	v_sub_f32_e32 v74, v18, v19
	ds_read2st64_b32 v[18:19], v70 offset0:36 offset1:37
	v_mov_b32_e32 v20, v22
	s_waitcnt lgkmcnt(0)
	v_mov_b32_e32 v69, v18
	v_pk_mul_f32 v[20:21], v[20:21], v[68:69]
	v_mov_b32_e32 v69, v19
	v_sub_f32_e32 v22, v20, v21
	v_mov_b32_e32 v20, v23
	v_mov_b32_e32 v21, v66
	v_pk_mul_f32 v[18:19], v[20:21], v[68:69]
	v_mov_b32_e32 v20, v24
	v_sub_f32_e32 v23, v18, v19
	ds_read2st64_b32 v[18:19], v70 offset0:38 offset1:39
	s_waitcnt lgkmcnt(0)
	v_mov_b32_e32 v69, v18
	v_pk_mul_f32 v[20:21], v[20:21], v[68:69]
	v_mov_b32_e32 v69, v19
	v_sub_f32_e32 v24, v20, v21
	v_mov_b32_e32 v20, v25
	v_mov_b32_e32 v21, v66
	v_pk_mul_f32 v[18:19], v[20:21], v[68:69]
	v_mov_b32_e32 v20, v26
	v_sub_f32_e32 v25, v18, v19
	ds_read2st64_b32 v[18:19], v70 offset0:40 offset1:41
	s_waitcnt lgkmcnt(0)
	v_mov_b32_e32 v69, v18
	v_pk_mul_f32 v[20:21], v[20:21], v[68:69]
	v_mov_b32_e32 v69, v19
	v_sub_f32_e32 v26, v20, v21
	v_mov_b32_e32 v20, v27
	v_mov_b32_e32 v21, v66
	v_pk_mul_f32 v[18:19], v[20:21], v[68:69]
	v_mov_b32_e32 v20, v28
	v_sub_f32_e32 v27, v18, v19
	ds_read2st64_b32 v[18:19], v70 offset0:42 offset1:43
	s_waitcnt lgkmcnt(0)
	v_mov_b32_e32 v69, v18
	v_pk_mul_f32 v[20:21], v[20:21], v[68:69]
	v_mov_b32_e32 v69, v19
	v_sub_f32_e32 v28, v20, v21
	v_mov_b32_e32 v20, v29
	v_mov_b32_e32 v21, v66
	v_pk_mul_f32 v[18:19], v[20:21], v[68:69]
	v_mov_b32_e32 v20, v30
	v_sub_f32_e32 v29, v18, v19
	ds_read2st64_b32 v[18:19], v70 offset0:44 offset1:45
	s_waitcnt lgkmcnt(0)
	v_mov_b32_e32 v69, v18
	v_pk_mul_f32 v[20:21], v[20:21], v[68:69]
	v_mov_b32_e32 v69, v19
	v_sub_f32_e32 v30, v20, v21
	v_mov_b32_e32 v20, v31
	v_mov_b32_e32 v21, v66
	v_pk_mul_f32 v[18:19], v[20:21], v[68:69]
	v_mov_b32_e32 v20, v32
	v_sub_f32_e32 v31, v18, v19
	ds_read2st64_b32 v[18:19], v70 offset0:46 offset1:47
	s_waitcnt lgkmcnt(0)
	v_mov_b32_e32 v69, v18
	v_pk_mul_f32 v[20:21], v[20:21], v[68:69]
	v_mov_b32_e32 v69, v19
	v_sub_f32_e32 v32, v20, v21
	v_mov_b32_e32 v20, v33
	v_mov_b32_e32 v21, v66
	v_pk_mul_f32 v[18:19], v[20:21], v[68:69]
	v_mov_b32_e32 v20, v2
	v_sub_f32_e32 v33, v18, v19
	ds_read2st64_b32 v[18:19], v70 offset0:48 offset1:49
	v_mov_b32_e32 v2, v3
	v_mov_b32_e32 v3, v66
	s_waitcnt lgkmcnt(0)
	v_mov_b32_e32 v69, v18
	v_pk_mul_f32 v[20:21], v[20:21], v[68:69]
	v_mov_b32_e32 v69, v19
	v_pk_mul_f32 v[2:3], v[2:3], v[68:69]
	v_mov_b32_e32 v18, v4
	v_sub_f32_e32 v76, v2, v3
	ds_read2st64_b32 v[2:3], v70 offset0:50 offset1:51
	v_mov_b32_e32 v19, v66
	v_mov_b32_e32 v4, v5
	v_mov_b32_e32 v5, v66
	v_sub_f32_e32 v75, v20, v21
	s_waitcnt lgkmcnt(0)
	v_mov_b32_e32 v69, v2
	v_pk_mul_f32 v[18:19], v[18:19], v[68:69]
	v_mov_b32_e32 v69, v3
	v_pk_mul_f32 v[2:3], v[4:5], v[68:69]
	v_mov_b32_e32 v4, v6
	v_sub_f32_e32 v78, v2, v3
	ds_read2st64_b32 v[2:3], v70 offset0:52 offset1:53
	v_mov_b32_e32 v6, v9
	v_mov_b32_e32 v9, v66
	v_sub_f32_e32 v77, v18, v19
	s_waitcnt lgkmcnt(0)
	v_mov_b32_e32 v69, v2
	v_pk_mul_f32 v[4:5], v[4:5], v[68:69]
	v_mov_b32_e32 v69, v3
	v_sub_f32_e32 v79, v4, v5
	v_mov_b32_e32 v4, v7
	v_mov_b32_e32 v5, v66
	v_pk_mul_f32 v[2:3], v[4:5], v[68:69]
	v_mov_b32_e32 v4, v8
	v_sub_f32_e32 v80, v2, v3
	ds_read2st64_b32 v[2:3], v70 offset0:54 offset1:55
	v_mov_b32_e32 v7, v66
	v_mov_b32_e32 v8, v11
	v_mov_b32_e32 v11, v66
	s_waitcnt lgkmcnt(0)
	v_mov_b32_e32 v69, v2
	v_pk_mul_f32 v[4:5], v[4:5], v[68:69]
	v_mov_b32_e32 v69, v3
	v_pk_mul_f32 v[2:3], v[6:7], v[68:69]
	v_mov_b32_e32 v6, v4
	v_mov_b32_e32 v7, v2
	v_mov_b32_e32 v2, v5
	ds_read2st64_b32 v[4:5], v70 offset0:56 offset1:57
	v_pk_add_f32 v[2:3], v[6:7], v[2:3] neg_lo:[0,1] neg_hi:[0,1]
	v_mov_b32_e32 v6, v10
	v_mov_b32_e32 v7, v66
	v_mov_b32_e32 v10, v13
	s_waitcnt lgkmcnt(0)
	v_mov_b32_e32 v69, v4
	v_pk_mul_f32 v[6:7], v[6:7], v[68:69]
	v_mov_b32_e32 v69, v5
	v_pk_mul_f32 v[4:5], v[8:9], v[68:69]
	v_mov_b32_e32 v8, v6
	v_mov_b32_e32 v9, v4
	v_mov_b32_e32 v4, v7
	ds_read2st64_b32 v[6:7], v70 offset0:58 offset1:59
	v_pk_add_f32 v[4:5], v[8:9], v[4:5] neg_lo:[0,1] neg_hi:[0,1]
	v_mov_b32_e32 v8, v12
	v_mov_b32_e32 v9, v66
	v_pk_mul_f32 v[18:19], v[2:3], v[2:3]
	s_waitcnt lgkmcnt(0)
	v_mov_b32_e32 v69, v6
	v_pk_mul_f32 v[8:9], v[8:9], v[68:69]
	v_mov_b32_e32 v69, v7
	v_pk_mul_f32 v[6:7], v[10:11], v[68:69]
	v_mov_b32_e32 v10, v8
	v_mov_b32_e32 v11, v6
	v_mov_b32_e32 v6, v9
	ds_read2st64_b32 v[8:9], v70 offset0:60 offset1:61
	v_pk_add_f32 v[6:7], v[10:11], v[6:7] neg_lo:[0,1] neg_hi:[0,1]
	v_mov_b32_e32 v10, v14
	v_mov_b32_e32 v11, v66
	v_mov_b32_e32 v14, v15
	s_waitcnt lgkmcnt(0)
	v_mov_b32_e32 v69, v8
	v_pk_mul_f32 v[10:11], v[10:11], v[68:69]
	v_mov_b32_e32 v15, v66
	v_mov_b32_e32 v69, v9
	v_pk_mul_f32 v[8:9], v[14:15], v[68:69]
	v_mov_b32_e32 v14, v10
	v_mov_b32_e32 v15, v8
	v_mov_b32_e32 v8, v11
	ds_read2st64_b32 v[10:11], v70 offset0:62 offset1:63
	v_pk_mul_f32 v[20:21], v[4:5], v[4:5]
	v_pk_mul_f32 v[12:13], v[6:7], v[6:7]
	v_pk_add_f32 v[8:9], v[14:15], v[8:9] neg_lo:[0,1] neg_hi:[0,1]
	s_waitcnt lgkmcnt(0)
	v_pk_mul_f32 v[10:11], v[66:67], v[10:11] op_sel_hi:[0,1]
	v_mul_f32_e32 v66, v50, v50
	v_fmac_f32_e32 v66, v51, v51
	v_fmac_f32_e32 v66, v52, v52
	v_fmac_f32_e32 v66, v53, v53
	v_fmac_f32_e32 v66, v54, v54
	v_fmac_f32_e32 v66, v55, v55
	v_fmac_f32_e32 v66, v56, v56
	v_fmac_f32_e32 v66, v57, v57
	v_fmac_f32_e32 v66, v58, v58
	v_fmac_f32_e32 v66, v59, v59
	v_fmac_f32_e32 v66, v60, v60
	v_fmac_f32_e32 v66, v61, v61
	v_fmac_f32_e32 v66, v62, v62
	v_fmac_f32_e32 v66, v63, v63
	v_fmac_f32_e32 v66, v64, v64
	v_fmac_f32_e32 v66, v65, v65
	v_fmac_f32_e32 v66, v34, v34
	v_fmac_f32_e32 v66, v35, v35
	v_fmac_f32_e32 v66, v36, v36
	v_fmac_f32_e32 v66, v37, v37
	v_fmac_f32_e32 v66, v38, v38
	v_fmac_f32_e32 v66, v39, v39
	v_fmac_f32_e32 v66, v40, v40
	v_fmac_f32_e32 v66, v41, v41
	v_fmac_f32_e32 v66, v42, v42
	v_fmac_f32_e32 v66, v43, v43
	v_fmac_f32_e32 v66, v44, v44
	v_fmac_f32_e32 v66, v45, v45
	v_fmac_f32_e32 v66, v46, v46
	v_fmac_f32_e32 v66, v47, v47
	v_fmac_f32_e32 v66, v48, v48
	v_fmac_f32_e32 v66, v49, v49
	v_fmac_f32_e32 v66, v71, v71
	v_fmac_f32_e32 v66, v72, v72
	v_fmac_f32_e32 v66, v73, v73
	v_fmac_f32_e32 v66, v74, v74
	v_fmac_f32_e32 v66, v22, v22
	v_fmac_f32_e32 v66, v23, v23
	v_fmac_f32_e32 v66, v24, v24
	v_fmac_f32_e32 v66, v25, v25
	v_fmac_f32_e32 v66, v26, v26
	v_fmac_f32_e32 v66, v27, v27
	v_fmac_f32_e32 v66, v28, v28
	v_fmac_f32_e32 v66, v29, v29
	v_fmac_f32_e32 v66, v30, v30
	v_fmac_f32_e32 v66, v31, v31
	v_fmac_f32_e32 v66, v32, v32
	v_fmac_f32_e32 v66, v33, v33
	v_fmac_f32_e32 v66, v75, v75
	v_fmac_f32_e32 v66, v76, v76
	v_fmac_f32_e32 v66, v77, v77
	v_fmac_f32_e32 v66, v78, v78
	v_fmac_f32_e32 v66, v79, v79
	v_fmac_f32_e32 v66, v80, v80
	v_add_f32_e32 v18, v66, v18
	v_add_f32_e32 v18, v18, v19
	v_add_f32_e32 v18, v18, v20
	v_add_f32_e32 v18, v18, v21
	v_add_f32_e32 v12, v18, v12
	v_pk_mul_f32 v[14:15], v[8:9], v[8:9]
	v_add_f32_e32 v12, v12, v13
	v_pk_fma_f32 v[10:11], v[16:17], v[68:69], v[10:11] op_sel_hi:[1,0,1] neg_lo:[0,0,1] neg_hi:[0,0,1]
	v_add_f32_e32 v12, v12, v14
	v_pk_mul_f32 v[16:17], v[10:11], v[10:11]
	v_add_f32_e32 v12, v12, v15
	v_add_f32_e32 v12, v12, v16
	v_add_f32_e32 v12, v12, v17
	ds_bpermute_b32 v0, v0, v12
	v_lshlrev_b64 v[20:21], 10, v[132:133]
	v_lshl_add_u64 v[20:21], s[38:39], 0, v[20:21]
	s_waitcnt lgkmcnt(0)
	v_add_f32_e32 v0, v12, v0
	v_fmamk_f32 v0, v0, 0x3c000000, v210
	v_cmp_gt_f32_e32 vcc, s35, v0
	v_mul_f32_e32 v12, 0x4b800000, v0
	s_nop 0
	v_cndmask_b32_e32 v0, v0, v12, vcc
	v_rsq_f32_e32 v0, v0
	s_nop 0
	v_mul_f32_e32 v12, 0x45800000, v0
	v_cndmask_b32_e32 v0, v0, v12, vcc
	global_load_dwordx4 v[12:15], v130, s[0:1]
	global_load_dwordx4 v[16:19], v130, s[0:1] offset:32
	global_load_dwordx4 v[82:85], v130, s[0:1] offset:64
	global_load_dwordx4 v[86:89], v130, s[0:1] offset:96
	global_load_dwordx4 v[90:93], v130, s[0:1] offset:128
	global_load_dwordx4 v[94:97], v130, s[0:1] offset:160
	global_load_dwordx4 v[98:101], v130, s[0:1] offset:192
	global_load_dwordx4 v[102:105], v130, s[0:1] offset:224
	global_load_dwordx4 v[106:109], v130, s[0:1] offset:256
	global_load_dwordx4 v[110:113], v130, s[0:1] offset:288
	global_load_dwordx4 v[114:117], v130, s[0:1] offset:320
	global_load_dwordx4 v[118:121], v130, s[0:1] offset:352
	global_load_dwordx4 v[122:125], v130, s[0:1] offset:384
	global_load_dwordx4 v[126:129], v130, s[0:1] offset:416
	global_load_dwordx4 v[136:139], v130, s[0:1] offset:448
	s_nop 0
	global_load_dwordx4 v[130:133], v130, s[0:1] offset:480
	v_mul_f32_e32 v66, v67, v0
	v_lshlrev_b32_e32 v0, 4, v135
	v_lshl_add_u64 v[20:21], v[20:21], 0, v[0:1]
	v_mul_f32_e32 v0, v50, v66
	s_waitcnt vmcnt(15)
	v_mul_f32_e32 v0, v12, v0
	v_mul_f32_e32 v12, v51, v66
	v_mul_f32_e32 v12, v13, v12
	v_cvt_pk_bf16_f32 v12, v0, v12
	v_mul_f32_e32 v0, v52, v66
	v_mul_f32_e32 v13, v53, v66
	v_mul_f32_e32 v0, v14, v0
	v_mul_f32_e32 v13, v15, v13
	v_cvt_pk_bf16_f32 v13, v0, v13
	v_mul_f32_e32 v0, v54, v66
	v_mul_f32_e32 v14, v55, v66
	s_waitcnt vmcnt(14)
	v_mul_f32_e32 v0, v16, v0
	v_mul_f32_e32 v14, v17, v14
	v_cvt_pk_bf16_f32 v14, v0, v14
	v_mul_f32_e32 v0, v56, v66
	v_mul_f32_e32 v15, v57, v66
	v_mul_f32_e32 v0, v18, v0
	v_mul_f32_e32 v15, v19, v15
	v_cvt_pk_bf16_f32 v15, v0, v15
	s_nop 1
	v_permlane32_swap_b32_e32 v12, v14
	v_permlane32_swap_b32_e32 v13, v15
	global_store_dwordx4 v[20:21], v[12:15], off
	s_nop 0
	v_mul_f32_e32 v0, v58, v66
	v_mul_f32_e32 v12, v59, v66
	s_waitcnt vmcnt(14)
	v_mul_f32_e32 v0, v82, v0
	v_mul_f32_e32 v12, v83, v12
	v_cvt_pk_bf16_f32 v12, v0, v12
	v_mul_f32_e32 v0, v60, v66
	v_mul_f32_e32 v13, v61, v66
	v_mul_f32_e32 v0, v84, v0
	v_mul_f32_e32 v13, v85, v13
	v_cvt_pk_bf16_f32 v13, v0, v13
	v_mul_f32_e32 v0, v62, v66
	v_mul_f32_e32 v14, v63, v66
	s_waitcnt vmcnt(13)
	v_mul_f32_e32 v0, v86, v0
	v_mul_f32_e32 v14, v87, v14
	v_cvt_pk_bf16_f32 v14, v0, v14
	v_mul_f32_e32 v0, v64, v66
	v_mul_f32_e32 v15, v65, v66
	v_mul_f32_e32 v0, v88, v0
	v_mul_f32_e32 v15, v89, v15
	v_cvt_pk_bf16_f32 v15, v0, v15
	s_nop 1
	v_permlane32_swap_b32_e32 v12, v14
	v_permlane32_swap_b32_e32 v13, v15
	global_store_dwordx4 v[20:21], v[12:15], off offset:32
	s_nop 0
	v_mul_f32_e32 v0, v34, v66
	v_mul_f32_e32 v12, v35, v66
	s_waitcnt vmcnt(13)
	v_mul_f32_e32 v0, v90, v0
	v_mul_f32_e32 v12, v91, v12
	v_cvt_pk_bf16_f32 v12, v0, v12
	v_mul_f32_e32 v0, v36, v66
	v_mul_f32_e32 v13, v37, v66
	v_mul_f32_e32 v0, v92, v0
	v_mul_f32_e32 v13, v93, v13
	v_cvt_pk_bf16_f32 v13, v0, v13
	v_mul_f32_e32 v0, v38, v66
	v_mul_f32_e32 v14, v39, v66
	s_waitcnt vmcnt(12)
	v_mul_f32_e32 v0, v94, v0
	v_mul_f32_e32 v14, v95, v14
	v_cvt_pk_bf16_f32 v14, v0, v14
	v_mul_f32_e32 v0, v40, v66
	v_mul_f32_e32 v15, v41, v66
	v_mul_f32_e32 v0, v96, v0
	v_mul_f32_e32 v15, v97, v15
	v_cvt_pk_bf16_f32 v15, v0, v15
	s_nop 1
	v_permlane32_swap_b32_e32 v12, v14
	v_permlane32_swap_b32_e32 v13, v15
	global_store_dwordx4 v[20:21], v[12:15], off offset:64
	s_nop 0
	v_mul_f32_e32 v0, v42, v66
	v_mul_f32_e32 v12, v43, v66
	s_waitcnt vmcnt(12)
	v_mul_f32_e32 v0, v98, v0
	v_mul_f32_e32 v12, v99, v12
	v_cvt_pk_bf16_f32 v12, v0, v12
	v_mul_f32_e32 v0, v44, v66
	v_mul_f32_e32 v13, v45, v66
	v_mul_f32_e32 v0, v100, v0
	v_mul_f32_e32 v13, v101, v13
	v_cvt_pk_bf16_f32 v13, v0, v13
	v_mul_f32_e32 v0, v46, v66
	v_mul_f32_e32 v14, v47, v66
	s_waitcnt vmcnt(11)
	v_mul_f32_e32 v0, v102, v0
	v_mul_f32_e32 v14, v103, v14
	v_cvt_pk_bf16_f32 v14, v0, v14
	v_mul_f32_e32 v0, v48, v66
	v_mul_f32_e32 v15, v49, v66
	v_mul_f32_e32 v0, v104, v0
	v_mul_f32_e32 v15, v105, v15
	v_cvt_pk_bf16_f32 v15, v0, v15
	s_nop 1
	v_permlane32_swap_b32_e32 v12, v14
	v_permlane32_swap_b32_e32 v13, v15
	global_store_dwordx4 v[20:21], v[12:15], off offset:96
	s_nop 0
	v_mul_f32_e32 v0, v71, v66
	v_mul_f32_e32 v12, v72, v66
	s_waitcnt vmcnt(11)
	v_mul_f32_e32 v0, v106, v0
	v_mul_f32_e32 v12, v107, v12
	v_cvt_pk_bf16_f32 v12, v0, v12
	v_mul_f32_e32 v0, v73, v66
	v_mul_f32_e32 v13, v74, v66
	v_mul_f32_e32 v0, v108, v0
	v_mul_f32_e32 v13, v109, v13
	v_cvt_pk_bf16_f32 v13, v0, v13
	v_mul_f32_e32 v0, v22, v66
	v_mul_f32_e32 v14, v23, v66
	s_waitcnt vmcnt(10)
	v_mul_f32_e32 v0, v110, v0
	v_mul_f32_e32 v14, v111, v14
	v_cvt_pk_bf16_f32 v14, v0, v14
	v_mul_f32_e32 v0, v24, v66
	v_mul_f32_e32 v15, v25, v66
	v_mul_f32_e32 v0, v112, v0
	v_mul_f32_e32 v15, v113, v15
	v_cvt_pk_bf16_f32 v15, v0, v15
	s_nop 1
	v_permlane32_swap_b32_e32 v12, v14
	v_permlane32_swap_b32_e32 v13, v15
	global_store_dwordx4 v[20:21], v[12:15], off offset:128
	s_nop 0
	v_mul_f32_e32 v0, v26, v66
	v_mul_f32_e32 v12, v27, v66
	s_waitcnt vmcnt(10)
	v_mul_f32_e32 v0, v114, v0
	v_mul_f32_e32 v12, v115, v12
	v_cvt_pk_bf16_f32 v12, v0, v12
	v_mul_f32_e32 v0, v28, v66
	v_mul_f32_e32 v13, v29, v66
	v_mul_f32_e32 v0, v116, v0
	v_mul_f32_e32 v13, v117, v13
	v_cvt_pk_bf16_f32 v13, v0, v13
	v_mul_f32_e32 v0, v30, v66
	v_mul_f32_e32 v14, v31, v66
	s_waitcnt vmcnt(9)
	v_mul_f32_e32 v0, v0, v118
	v_mul_f32_e32 v14, v14, v119
	v_cvt_pk_bf16_f32 v14, v0, v14
	v_mul_f32_e32 v0, v32, v66
	v_mul_f32_e32 v15, v33, v66
	v_mul_f32_e32 v0, v0, v120
	v_mul_f32_e32 v15, v15, v121
	v_cvt_pk_bf16_f32 v15, v0, v15
	s_nop 1
	v_permlane32_swap_b32_e32 v12, v14
	v_permlane32_swap_b32_e32 v13, v15
	global_store_dwordx4 v[20:21], v[12:15], off offset:160
	s_nop 0
	v_mul_f32_e32 v0, v75, v66
	v_mul_f32_e32 v12, v76, v66
	s_waitcnt vmcnt(9)
	v_mul_f32_e32 v0, v0, v122
	v_mul_f32_e32 v12, v12, v123
	v_cvt_pk_bf16_f32 v12, v0, v12
	v_mul_f32_e32 v0, v77, v66
	v_mul_f32_e32 v13, v78, v66
	v_mul_f32_e32 v0, v0, v124
	v_mul_f32_e32 v13, v13, v125
	v_cvt_pk_bf16_f32 v13, v0, v13
	v_mul_f32_e32 v0, v79, v66
	v_mul_f32_e32 v14, v80, v66
	s_waitcnt vmcnt(8)
	v_mul_f32_e32 v0, v0, v126
	v_mul_f32_e32 v14, v14, v127
	v_cvt_pk_bf16_f32 v14, v0, v14
	v_mul_f32_e32 v0, v2, v66
	v_mul_f32_e32 v2, v3, v66
	v_mul_f32_e32 v0, v0, v128
	v_mul_f32_e32 v2, v2, v129
	v_cvt_pk_bf16_f32 v15, v0, v2
	s_nop 1
	v_permlane32_swap_b32_e32 v12, v14
	v_permlane32_swap_b32_e32 v13, v15
	global_store_dwordx4 v[20:21], v[12:15], off offset:192
	v_mul_f32_e32 v0, v4, v66
	v_mul_f32_e32 v2, v5, v66
	s_waitcnt vmcnt(8)
	v_mul_f32_e32 v0, v0, v136
	v_mul_f32_e32 v2, v2, v137
	v_cvt_pk_bf16_f32 v12, v0, v2
	v_mul_f32_e32 v0, v6, v66
	v_mul_f32_e32 v3, v7, v66
	v_mul_f32_e32 v0, v0, v138
	v_mul_f32_e32 v3, v3, v139
	v_cvt_pk_bf16_f32 v13, v0, v3
	v_mul_f32_e32 v0, v8, v66
	v_mul_f32_e32 v2, v9, v66
	s_waitcnt vmcnt(7)
	v_mul_f32_e32 v0, v0, v130
	v_mul_f32_e32 v2, v2, v131
	v_mul_f32_e32 v3, v11, v66
	v_cvt_pk_bf16_f32 v14, v0, v2
	v_mul_f32_e32 v0, v10, v66
	v_mul_f32_e32 v3, v3, v133
	v_mul_f32_e32 v0, v0, v132
	v_cvt_pk_bf16_f32 v15, v0, v3
	s_nop 1
	v_permlane32_swap_b32_e32 v12, v14
	v_permlane32_swap_b32_e32 v13, v15
	global_store_dwordx4 v[20:21], v[12:15], off offset:224
	s_branch .LBB0_460
